# background cache copy issued after the first counted wait of the K-loop iteration (only one wait becomes stricter)
# speedup vs baseline: 1.0169x; 1.0036x over previous
.LBB0_688:
	s_add_u32 s20, s44, s18
	s_addc_u32 s21, s45, s19
	s_add_u32 s20, s20, 0x5000100
	s_addc_u32 s21, s21, 0
	s_add_u32 s49, s46, s18
	s_addc_u32 s50, s47, s19
	s_add_i32 s51, 0, 0x10000
	s_cmpk_eq_i32 s18, 0x700
	s_cselect_b32 s23, s39, s21
	s_cselect_b32 s22, s17, s20
	v_add_u32_e32 v144, s51, v148
	s_cselect_b32 s21, s43, s50
	s_cselect_b32 s20, s42, s49
	s_add_i32 s49, 0, 0x14000
	ds_read_b128 v[140:143], v144
	ds_read_b128 v[154:157], v144 offset:1024
	ds_read_b128 v[158:161], v144 offset:2048
	ds_read_b128 v[162:165], v144 offset:3072
	v_add_u32_e32 v144, s49, v148
	ds_read_b128 v[166:169], v144
	ds_read_b128 v[170:173], v144 offset:1024
	ds_read_b128 v[174:177], v144 offset:2048
	ds_read_b128 v[178:181], v144 offset:3072
	v_lshl_add_u64 v[144:145], v[136:137], 0, s[18:19]
	s_add_i32 m0, s24, 0xc000
	ds_read_b128 v[182:185], v152
	ds_read_b128 v[186:189], v152 offset:1024
	ds_read_b128 v[190:193], v152 offset:2048
	ds_read_b128 v[196:199], v152 offset:3072
	ds_read_b128 v[202:205], v152 offset:4096
	ds_read_b128 v[206:209], v152 offset:5120
	ds_read_b128 v[210:213], v152 offset:6144
	ds_read_b128 v[214:217], v152 offset:7168
	global_load_lds_dwordx4 v[144:145], off
	v_lshl_add_u64 v[144:145], v[138:139], 0, s[18:19]
	s_add_i32 m0, s24, 0xe000
	s_nop 0
	global_load_lds_dwordx4 v[144:145], off
	s_waitcnt vmcnt(8)
	s_waitcnt lgkmcnt(0)
	s_barrier
	s_setprio 1
	s_waitcnt lgkmcnt(0)
	v_mfma_f32_16x16x32_bf16 v[126:129], v[140:143], v[182:185], v[126:129]
	v_mfma_f32_16x16x32_bf16 v[122:125], v[158:161], v[182:185], v[122:125]
	v_mfma_f32_16x16x32_bf16 v[110:113], v[140:143], v[190:193], v[110:113]
	v_mfma_f32_16x16x32_bf16 v[106:109], v[158:161], v[190:193], v[106:109]
	v_mfma_f32_16x16x32_bf16 v[94:97], v[140:143], v[202:205], v[94:97]
	v_mfma_f32_16x16x32_bf16 v[90:93], v[158:161], v[202:205], v[90:93]
	v_mfma_f32_16x16x32_bf16 v[78:81], v[140:143], v[210:213], v[78:81]
	v_mfma_f32_16x16x32_bf16 v[74:77], v[158:161], v[210:213], v[74:77]
	v_mfma_f32_16x16x32_bf16 v[126:129], v[154:157], v[186:189], v[126:129]
	v_mfma_f32_16x16x32_bf16 v[122:125], v[162:165], v[186:189], v[122:125]
	v_mfma_f32_16x16x32_bf16 v[110:113], v[154:157], v[196:199], v[110:113]
	v_mfma_f32_16x16x32_bf16 v[106:109], v[162:165], v[196:199], v[106:109]
	v_mfma_f32_16x16x32_bf16 v[94:97], v[154:157], v[206:209], v[94:97]
	v_mfma_f32_16x16x32_bf16 v[90:93], v[162:165], v[206:209], v[90:93]
	v_mfma_f32_16x16x32_bf16 v[78:81], v[154:157], v[214:217], v[78:81]
	v_mfma_f32_16x16x32_bf16 v[74:77], v[162:165], v[214:217], v[74:77]
	s_setprio 0
	s_setprio 1
	v_mfma_f32_16x16x32_bf16 v[118:121], v[166:169], v[182:185], v[118:121]
	v_mfma_f32_16x16x32_bf16 v[114:117], v[174:177], v[182:185], v[114:117]
	v_mfma_f32_16x16x32_bf16 v[102:105], v[166:169], v[190:193], v[102:105]
	v_mfma_f32_16x16x32_bf16 v[98:101], v[174:177], v[190:193], v[98:101]
	v_mfma_f32_16x16x32_bf16 v[86:89], v[166:169], v[202:205], v[86:89]
	v_mfma_f32_16x16x32_bf16 v[82:85], v[174:177], v[202:205], v[82:85]
	v_mfma_f32_16x16x32_bf16 v[70:73], v[166:169], v[210:213], v[70:73]
	v_mfma_f32_16x16x32_bf16 v[66:69], v[174:177], v[210:213], v[66:69]
	v_mfma_f32_16x16x32_bf16 v[118:121], v[170:173], v[186:189], v[118:121]
	v_mfma_f32_16x16x32_bf16 v[114:117], v[178:181], v[186:189], v[114:117]
	v_mfma_f32_16x16x32_bf16 v[102:105], v[170:173], v[196:199], v[102:105]
	v_mfma_f32_16x16x32_bf16 v[98:101], v[178:181], v[196:199], v[98:101]
	v_mfma_f32_16x16x32_bf16 v[86:89], v[170:173], v[206:209], v[86:89]
	v_mfma_f32_16x16x32_bf16 v[82:85], v[178:181], v[206:209], v[82:85]
	v_mfma_f32_16x16x32_bf16 v[70:73], v[170:173], v[214:217], v[70:73]
	v_mfma_f32_16x16x32_bf16 v[66:69], v[178:181], v[214:217], v[66:69]
	s_setprio 0
	s_barrier
	s_cmp_eq_u32 s99, 0
	s_cbranch_scc1 .Lbgc_it_skip
	s_mov_b64 exec, s[100:101]
	s_nop 0
	global_store_dwordx4 v[230:231], v[232:235], off nt
	s_mov_b64 exec, -1
	v_add_u32_e32 v226, 64, v226
	v_add_u32_e32 v227, 1, v227
	v_cmp_le_i32_e32 vcc, 0x1ffc0, v226
	v_subrev_u32_e32 v236, 0x1ffc0, v226
	s_nop 0
	v_cndmask_b32_e32 v226, v226, v236, vcc
	v_cndmask_b32_e64 v238, 0, 1, vcc
	v_add_u32_e32 v227, v227, v238
	v_mov_b32_e32 v236, 0x200400
	v_mov_b32_e32 v238, 0x200800
	v_cndmask_b32_e32 v236, v236, v238, vcc
	v_lshl_add_u64 v[228:229], v[228:229], 0, v[236:237]
	v_lshl_add_u64 v[230:231], v[230:231], 0, v[236:237]
	v_cmp_gt_i32_e32 vcc, 64, v227
	s_nop 1
	s_mov_b64 s[100:101], vcc
	s_mov_b64 exec, vcc
	s_nop 0
	global_load_dwordx4 v[232:235], v[228:229], off nt
	s_mov_b64 exec, -1
	s_cmp_lg_u64 s[100:101], 0
	s_cselect_b32 s99, 1, 0
.Lbgc_it_skip:
	s_add_i32 s50, s51, s2
	v_lshl_add_u64 v[144:145], s[20:21], 0, v[0:1]
	s_mov_b32 m0, s50
	ds_read_b128 v[182:185], v152 offset:16384
	ds_read_b128 v[186:189], v152 offset:17408
	ds_read_b128 v[190:193], v152 offset:18432
	ds_read_b128 v[196:199], v152 offset:19456
	ds_read_b128 v[202:205], v152 offset:20480
	ds_read_b128 v[206:209], v152 offset:21504
	ds_read_b128 v[210:213], v152 offset:22528
	ds_read_b128 v[214:217], v152 offset:23552
	global_load_lds_dwordx4 v[144:145], off
	s_add_i32 m0, s50, 0x2000
	s_add_u32 s50, s20, 0x40000
	v_lshl_add_u64 v[218:219], s[20:21], 0, v[130:131]
	s_addc_u32 s51, s21, 0
	s_add_i32 s49, s49, s2
	global_load_lds_dwordx4 v[218:219], off
	v_lshl_add_u64 v[220:221], s[50:51], 0, v[0:1]
	s_mov_b32 m0, s49
	v_lshl_add_u64 v[222:223], s[22:23], 0, v[130:131]
	global_load_lds_dwordx4 v[220:221], off
	v_lshl_add_u64 v[220:221], s[50:51], 0, v[130:131]
	s_add_i32 m0, s49, 0x2000
	s_nop 0
	global_load_lds_dwordx4 v[220:221], off
	v_lshl_add_u64 v[220:221], s[22:23], 0, v[0:1]
	s_mov_b32 m0, s24
	s_nop 0
	global_load_lds_dwordx4 v[220:221], off
	s_mov_b32 m0, s25
	s_nop 0
	global_load_lds_dwordx4 v[222:223], off
	s_waitcnt vmcnt(8)
	s_waitcnt lgkmcnt(0)
	s_barrier
	s_setprio 1
	s_waitcnt lgkmcnt(0)
	v_mfma_f32_16x16x32_bf16 v[62:65], v[140:143], v[182:185], v[62:65]
	v_mfma_f32_16x16x32_bf16 v[58:61], v[158:161], v[182:185], v[58:61]
	v_mfma_f32_16x16x32_bf16 v[46:49], v[140:143], v[190:193], v[46:49]
	v_mfma_f32_16x16x32_bf16 v[42:45], v[158:161], v[190:193], v[42:45]
	v_mfma_f32_16x16x32_bf16 v[30:33], v[140:143], v[202:205], v[30:33]
	v_mfma_f32_16x16x32_bf16 v[26:29], v[158:161], v[202:205], v[26:29]
	v_mfma_f32_16x16x32_bf16 v[14:17], v[140:143], v[210:213], v[14:17]
	v_mfma_f32_16x16x32_bf16 v[10:13], v[158:161], v[210:213], v[10:13]
	v_mfma_f32_16x16x32_bf16 v[62:65], v[154:157], v[186:189], v[62:65]
	v_mfma_f32_16x16x32_bf16 v[58:61], v[162:165], v[186:189], v[58:61]
	v_mfma_f32_16x16x32_bf16 v[46:49], v[154:157], v[196:199], v[46:49]
	v_mfma_f32_16x16x32_bf16 v[42:45], v[162:165], v[196:199], v[42:45]
	v_mfma_f32_16x16x32_bf16 v[30:33], v[154:157], v[206:209], v[30:33]
	v_mfma_f32_16x16x32_bf16 v[26:29], v[162:165], v[206:209], v[26:29]
	v_mfma_f32_16x16x32_bf16 v[14:17], v[154:157], v[214:217], v[14:17]
	v_mfma_f32_16x16x32_bf16 v[10:13], v[162:165], v[214:217], v[10:13]
	s_setprio 0
	s_setprio 1
	v_mfma_f32_16x16x32_bf16 v[54:57], v[166:169], v[182:185], v[54:57]
	v_mfma_f32_16x16x32_bf16 v[50:53], v[174:177], v[182:185], v[50:53]
	v_mfma_f32_16x16x32_bf16 v[38:41], v[166:169], v[190:193], v[38:41]
	v_mfma_f32_16x16x32_bf16 v[34:37], v[174:177], v[190:193], v[34:37]
	v_mfma_f32_16x16x32_bf16 v[22:25], v[166:169], v[202:205], v[22:25]
	v_mfma_f32_16x16x32_bf16 v[18:21], v[174:177], v[202:205], v[18:21]
	v_mfma_f32_16x16x32_bf16 v[6:9], v[166:169], v[210:213], v[6:9]
	v_mfma_f32_16x16x32_bf16 v[2:5], v[174:177], v[210:213], v[2:5]
	v_mfma_f32_16x16x32_bf16 v[54:57], v[170:173], v[186:189], v[54:57]
	v_mfma_f32_16x16x32_bf16 v[50:53], v[178:181], v[186:189], v[50:53]
	v_mfma_f32_16x16x32_bf16 v[38:41], v[170:173], v[196:199], v[38:41]
	v_mfma_f32_16x16x32_bf16 v[34:37], v[178:181], v[196:199], v[34:37]
	v_mfma_f32_16x16x32_bf16 v[22:25], v[170:173], v[206:209], v[22:25]
	v_mfma_f32_16x16x32_bf16 v[18:21], v[178:181], v[206:209], v[18:21]
	v_mfma_f32_16x16x32_bf16 v[6:9], v[170:173], v[214:217], v[6:9]
	v_mfma_f32_16x16x32_bf16 v[2:5], v[178:181], v[214:217], v[2:5]
	s_setprio 0
	s_barrier
	s_add_i32 s49, 0, 0x18000
	v_add_u32_e32 v153, s49, v148
	s_add_i32 s50, 0, 0x1c000
	ds_read_b128 v[140:143], v153
	ds_read_b128 v[154:157], v153 offset:1024
	ds_read_b128 v[158:161], v153 offset:2048
	ds_read_b128 v[162:165], v153 offset:3072
	v_add_u32_e32 v153, s50, v148
	ds_read_b128 v[166:169], v153
	ds_read_b128 v[170:173], v153 offset:1024
	ds_read_b128 v[174:177], v153 offset:2048
	ds_read_b128 v[178:181], v153 offset:3072
	s_add_u32 s22, s22, 0x40000
	s_addc_u32 s23, s23, 0
	s_mov_b32 m0, s26
	v_lshl_add_u64 v[224:225], s[22:23], 0, v[0:1]
	ds_read_b128 v[182:185], v152 offset:32768
	ds_read_b128 v[186:189], v152 offset:33792
	ds_read_b128 v[190:193], v152 offset:34816
	ds_read_b128 v[196:199], v152 offset:35840
	ds_read_b128 v[202:205], v152 offset:36864
	ds_read_b128 v[206:209], v152 offset:37888
	ds_read_b128 v[210:213], v152 offset:38912
	ds_read_b128 v[214:217], v152 offset:39936
	global_load_lds_dwordx4 v[224:225], off
	v_lshl_add_u64 v[224:225], s[22:23], 0, v[130:131]
	s_mov_b32 m0, s27
	s_nop 0
	global_load_lds_dwordx4 v[224:225], off
	s_waitcnt vmcnt(8)
	s_waitcnt lgkmcnt(0)
	s_barrier
	s_setprio 1
	s_waitcnt lgkmcnt(0)
	v_mfma_f32_16x16x32_bf16 v[126:129], v[140:143], v[182:185], v[126:129]
	v_mfma_f32_16x16x32_bf16 v[122:125], v[158:161], v[182:185], v[122:125]
	v_mfma_f32_16x16x32_bf16 v[110:113], v[140:143], v[190:193], v[110:113]
	v_mfma_f32_16x16x32_bf16 v[106:109], v[158:161], v[190:193], v[106:109]
	v_mfma_f32_16x16x32_bf16 v[94:97], v[140:143], v[202:205], v[94:97]
	v_mfma_f32_16x16x32_bf16 v[90:93], v[158:161], v[202:205], v[90:93]
	v_mfma_f32_16x16x32_bf16 v[78:81], v[140:143], v[210:213], v[78:81]
	v_mfma_f32_16x16x32_bf16 v[74:77], v[158:161], v[210:213], v[74:77]
	v_mfma_f32_16x16x32_bf16 v[126:129], v[154:157], v[186:189], v[126:129]
	v_mfma_f32_16x16x32_bf16 v[122:125], v[162:165], v[186:189], v[122:125]
	v_mfma_f32_16x16x32_bf16 v[110:113], v[154:157], v[196:199], v[110:113]
	v_mfma_f32_16x16x32_bf16 v[106:109], v[162:165], v[196:199], v[106:109]
	v_mfma_f32_16x16x32_bf16 v[94:97], v[154:157], v[206:209], v[94:97]
	v_mfma_f32_16x16x32_bf16 v[90:93], v[162:165], v[206:209], v[90:93]
	v_mfma_f32_16x16x32_bf16 v[78:81], v[154:157], v[214:217], v[78:81]
	v_mfma_f32_16x16x32_bf16 v[74:77], v[162:165], v[214:217], v[74:77]
	s_setprio 0
	s_setprio 1
	v_mfma_f32_16x16x32_bf16 v[118:121], v[166:169], v[182:185], v[118:121]
	v_mfma_f32_16x16x32_bf16 v[114:117], v[174:177], v[182:185], v[114:117]
	v_mfma_f32_16x16x32_bf16 v[102:105], v[166:169], v[190:193], v[102:105]
	v_mfma_f32_16x16x32_bf16 v[98:101], v[174:177], v[190:193], v[98:101]
	v_mfma_f32_16x16x32_bf16 v[86:89], v[166:169], v[202:205], v[86:89]
	v_mfma_f32_16x16x32_bf16 v[82:85], v[174:177], v[202:205], v[82:85]
	v_mfma_f32_16x16x32_bf16 v[70:73], v[166:169], v[210:213], v[70:73]
	v_mfma_f32_16x16x32_bf16 v[66:69], v[174:177], v[210:213], v[66:69]
	v_mfma_f32_16x16x32_bf16 v[118:121], v[170:173], v[186:189], v[118:121]
	v_mfma_f32_16x16x32_bf16 v[114:117], v[178:181], v[186:189], v[114:117]
	v_mfma_f32_16x16x32_bf16 v[102:105], v[170:173], v[196:199], v[102:105]
	v_mfma_f32_16x16x32_bf16 v[98:101], v[178:181], v[196:199], v[98:101]
	v_mfma_f32_16x16x32_bf16 v[86:89], v[170:173], v[206:209], v[86:89]
	v_mfma_f32_16x16x32_bf16 v[82:85], v[178:181], v[206:209], v[82:85]
	v_mfma_f32_16x16x32_bf16 v[70:73], v[170:173], v[214:217], v[70:73]
	v_mfma_f32_16x16x32_bf16 v[66:69], v[178:181], v[214:217], v[66:69]
	s_setprio 0
	s_barrier
	s_add_i32 s22, s49, s2
	v_lshl_add_u64 v[144:145], v[144:145], 0, s[0:1]
	s_mov_b32 m0, s22
	ds_read_b128 v[182:185], v152 offset:49152
	ds_read_b128 v[186:189], v152 offset:50176
	ds_read_b128 v[190:193], v152 offset:51200
	ds_read_b128 v[196:199], v152 offset:52224
	ds_read_b128 v[202:205], v152 offset:53248
	ds_read_b128 v[206:209], v152 offset:54272
	ds_read_b128 v[210:213], v152 offset:55296
	ds_read_b128 v[214:217], v152 offset:56320
	global_load_lds_dwordx4 v[144:145], off
	s_add_i32 m0, s22, 0x2000
	s_add_u32 s20, s20, 0x40080
	v_lshl_add_u64 v[144:145], v[218:219], 0, s[0:1]
	s_addc_u32 s21, s21, 0
	s_add_i32 s22, s50, s2
	global_load_lds_dwordx4 v[144:145], off
	v_lshl_add_u64 v[144:145], s[20:21], 0, v[0:1]
	s_mov_b32 m0, s22
	s_nop 0
	global_load_lds_dwordx4 v[144:145], off
	v_lshl_add_u64 v[144:145], s[20:21], 0, v[130:131]
	s_add_i32 m0, s22, 0x2000
	s_nop 0
	global_load_lds_dwordx4 v[144:145], off
	v_lshl_add_u64 v[144:145], v[220:221], 0, s[0:1]
	s_mov_b32 m0, s28
	s_nop 0
	global_load_lds_dwordx4 v[144:145], off
	v_lshl_add_u64 v[144:145], v[222:223], 0, s[0:1]
	s_mov_b32 m0, s29
	s_nop 0
	global_load_lds_dwordx4 v[144:145], off
	s_waitcnt vmcnt(8)
	s_waitcnt lgkmcnt(0)
	s_barrier
	s_setprio 1
	s_waitcnt lgkmcnt(0)
	v_mfma_f32_16x16x32_bf16 v[62:65], v[140:143], v[182:185], v[62:65]
	v_mfma_f32_16x16x32_bf16 v[58:61], v[158:161], v[182:185], v[58:61]
	v_mfma_f32_16x16x32_bf16 v[46:49], v[140:143], v[190:193], v[46:49]
	v_mfma_f32_16x16x32_bf16 v[42:45], v[158:161], v[190:193], v[42:45]
	v_mfma_f32_16x16x32_bf16 v[30:33], v[140:143], v[202:205], v[30:33]
	v_mfma_f32_16x16x32_bf16 v[26:29], v[158:161], v[202:205], v[26:29]
	v_mfma_f32_16x16x32_bf16 v[14:17], v[140:143], v[210:213], v[14:17]
	v_mfma_f32_16x16x32_bf16 v[10:13], v[158:161], v[210:213], v[10:13]
	v_mfma_f32_16x16x32_bf16 v[62:65], v[154:157], v[186:189], v[62:65]
	v_mfma_f32_16x16x32_bf16 v[58:61], v[162:165], v[186:189], v[58:61]
	v_mfma_f32_16x16x32_bf16 v[46:49], v[154:157], v[196:199], v[46:49]
	v_mfma_f32_16x16x32_bf16 v[42:45], v[162:165], v[196:199], v[42:45]
	v_mfma_f32_16x16x32_bf16 v[30:33], v[154:157], v[206:209], v[30:33]
	v_mfma_f32_16x16x32_bf16 v[26:29], v[162:165], v[206:209], v[26:29]
	v_mfma_f32_16x16x32_bf16 v[14:17], v[154:157], v[214:217], v[14:17]
	v_mfma_f32_16x16x32_bf16 v[10:13], v[162:165], v[214:217], v[10:13]
	s_setprio 0
	s_setprio 1
	v_mfma_f32_16x16x32_bf16 v[54:57], v[166:169], v[182:185], v[54:57]
	v_mfma_f32_16x16x32_bf16 v[50:53], v[174:177], v[182:185], v[50:53]
	v_mfma_f32_16x16x32_bf16 v[38:41], v[166:169], v[190:193], v[38:41]
	v_mfma_f32_16x16x32_bf16 v[34:37], v[174:177], v[190:193], v[34:37]
	v_mfma_f32_16x16x32_bf16 v[22:25], v[166:169], v[202:205], v[22:25]
	v_mfma_f32_16x16x32_bf16 v[18:21], v[174:177], v[202:205], v[18:21]
	v_mfma_f32_16x16x32_bf16 v[6:9], v[166:169], v[210:213], v[6:9]
	v_mfma_f32_16x16x32_bf16 v[2:5], v[174:177], v[210:213], v[2:5]
	v_mfma_f32_16x16x32_bf16 v[54:57], v[170:173], v[186:189], v[54:57]
	v_mfma_f32_16x16x32_bf16 v[50:53], v[178:181], v[186:189], v[50:53]
	v_mfma_f32_16x16x32_bf16 v[38:41], v[170:173], v[196:199], v[38:41]
	v_mfma_f32_16x16x32_bf16 v[34:37], v[178:181], v[196:199], v[34:37]
	v_mfma_f32_16x16x32_bf16 v[22:25], v[170:173], v[206:209], v[22:25]
	v_mfma_f32_16x16x32_bf16 v[18:21], v[178:181], v[206:209], v[18:21]
	v_mfma_f32_16x16x32_bf16 v[6:9], v[170:173], v[214:217], v[6:9]
	v_mfma_f32_16x16x32_bf16 v[2:5], v[178:181], v[214:217], v[2:5]
	s_setprio 0
	s_barrier
	s_add_i32 s48, s48, 2
	s_add_u32 s18, s18, 0x100
	s_addc_u32 s19, s19, 0
	s_cmp_gt_u32 s48, 13
	s_cbranch_scc0 .LBB0_688
	s_and_b64 vcc, exec, s[8:9]
	s_cbranch_vccz .LBB0_691
	s_barrier
